# P3: half of the workgroups run sample-group scan queues first (static queue halves)
# baseline (speedup 1.0000x reference)
.LBB0_678:
	s_bfe_u32 s0, s2, 0x10003
	s_lshl_b32 s1, s0, 7
	v_writelane_b32 v255, s0, 1
	v_writelane_b32 v255, s1, 0
	s_mov_b32 s1, 0
	s_nop 0
	v_writelane_b32 v255, s1, 2
	s_cmp_lt_i32 s92, 4
	s_cselect_b64 s[0:1], -1, 0
	s_cmp_gt_i32 s93, 3
	s_cselect_b64 s[4:5], -1, 0
	s_and_b64 s[0:1], s[0:1], s[4:5]
	s_andn2_b64 vcc, exec, s[0:1]
	s_cbranch_vccnz .LBB0_996
.Lp3_again:
	s_add_u32 s0, s86, 0x1dd00000
	s_addc_u32 s1, s87, 0
	s_add_u32 s20, s86, 0x200000
	s_addc_u32 s21, s87, 0
	s_add_u32 s4, s86, 0x500000
	s_addc_u32 s5, s87, 0
	s_add_u32 s37, s84, 0x4200000
	v_writelane_b32 v254, s92, 43
	s_addc_u32 s51, s85, 0
	s_cmp_lg_u32 s33, 3
	v_writelane_b32 v254, s93, 44
	v_writelane_b32 v254, s90, 45
	s_cselect_b64 s[6:7], -1, 0
	s_cmpk_gt_u32 s94, 0xff
	v_writelane_b32 v254, s91, 46
	s_cselect_b64 s[8:9], -1, 0
	s_lshl_b32 s10, s33, 4
	v_writelane_b32 v254, s10, 47
	s_and_b32 s10, s10, 0x3fffffe0
	s_lshl_b32 s3, s33, 5
	s_lshl_b32 s12, s10, 1
	s_and_b32 s95, s3, 32
	s_mov_b32 s27, s94
	s_add_i32 s94, s12, 0
	s_add_u32 s12, s72, 0x3000
	s_addc_u32 s13, s73, 0
	v_writelane_b32 v254, s12, 48
	s_mov_b32 s11, 0
	v_mov_b32_e32 v50, 0
	v_writelane_b32 v254, s13, 49
	s_add_u32 s12, s72, 0x6000
	s_addc_u32 s13, s73, 0
	v_writelane_b32 v254, s12, 50
	s_movk_i32 s58, 0x110
	s_movk_i32 s59, 0x800
	v_writelane_b32 v254, s13, 51
	s_add_u32 s12, s72, 0x9000
	s_addc_u32 s13, s73, 0
	s_add_u32 s50, s86, 0x24000000
	v_writelane_b32 v254, s12, 52
	s_addc_u32 s90, s87, 0
	s_sub_i32 s89, s10, 64
	v_writelane_b32 v254, s13, 53
	s_lshl_b32 s12, s89, 2
	s_add_i32 s92, s12, 0
	s_lshl_b32 s12, s95, 2
	s_add_i32 s93, s12, 0
	s_add_i32 s92, s92, 0x20e00
	s_add_i32 s93, s93, 0x1bc00
	s_cmpk_gt_u32 s27, 0xbf
	s_cselect_b64 s[12:13], -1, 0
	s_cmp_lt_u32 s27, 64
	s_cselect_b64 s[28:29], -1, 0
	s_and_b64 s[14:15], s[28:29], exec
	s_cselect_b32 s16, 0, 32
	s_cmp_eq_u32 s33, 1
	s_cselect_b32 s17, 32, 0
	s_lshl_b32 s14, s17, 2
	s_add_i32 s23, s14, 0
	s_add_i32 s22, s23, 0x20c00
	s_add_i32 s23, s23, 0x20d00
	s_lshl_b32 s24, s17, 1
	s_cmp_lg_u32 s33, 2
	s_cselect_b64 s[30:31], -1, 0
	s_lshl_b32 s14, s33, 12
	s_and_b32 s34, s14, 0x1000
	v_writelane_b32 v254, s27, 54
	s_bfe_u32 s14, s27, 0x10006
	s_lshr_b32 s91, s27, 7
	v_writelane_b32 v254, s14, 55
	s_mulk_i32 s14, 0x2200
	s_add_i32 s27, s14, 0
	s_mul_i32 s14, s91, 0x2200
	s_add_i32 s15, 0, 0x23d40
	s_lshl_b32 s25, s91, 2
	s_lshl_b32 s26, s91, 6
	s_add_i32 s27, s27, 0xf400
	s_add_i32 s14, s14, 0
	s_mov_b32 s36, 0xbfb8aa3b
	s_add_i32 s60, 0, 0x20f00
	s_movk_i32 s61, 0x90
	s_mov_b32 s62, 0x5040100
	s_add_i32 s63, 0, 0x17c00
	s_add_i32 s64, 0, 0x1fc00
	s_add_i32 s65, 0, 0x20efc
	s_lshl_b32 s38, s34, 2
	v_mov_b32_e32 v1, s15
	v_mov_b32_e32 v145, 0xfc00
	s_lshl_b32 s40, s10, 2
	s_branch .LBB0_682

.LBB0_682:
	v_readlane_b32 vcc_lo, v255, 1
	s_cmp_lg_u32 vcc_lo, 0
	s_cbranch_scc1 .LBB0_756
	s_mov_b64 s[34:35], exec
	v_readlane_b32 s42, v254, 7
	v_readlane_b32 s43, v254, 8
	s_and_b64 s[42:43], s[34:35], s[42:43]
	s_mov_b64 exec, s[42:43]
	s_cbranch_execz .LBB0_686
	s_mov_b64 s[44:45], exec
	v_mbcnt_lo_u32_b32 v2, s44, 0
	v_mbcnt_hi_u32_b32 v2, s45, v2
	v_cmp_eq_u32_e32 vcc, 0, v2
	s_and_saveexec_b64 s[42:43], vcc
	s_cbranch_execz .LBB0_685
	s_bcnt1_i32_b64 s10, s[44:45]
	v_mov_b32_e32 v3, s10
	global_atomic_add v3, v255, v3, s[86:87] offset:512 sc0

.LBB0_686:
	s_or_b64 exec, exec, s[34:35]
	s_waitcnt vmcnt(0) lgkmcnt(0)
	s_barrier
	ds_read_b32 v2, v1
	s_movk_i32 s10, 0x7f
	s_mov_b64 s[34:35], -1
	s_waitcnt lgkmcnt(0)
	s_barrier
	v_cmp_lt_i32_e32 vcc, s10, v2
	v_readfirstlane_b32 s42, v2
	s_cbranch_vccnz .LBB0_681
	s_bfe_u32 vcc_lo, s2, 0x10003
	s_lshl_b32 vcc_lo, vcc_lo, 7
	s_add_i32 s42, s42, vcc_lo
	v_mov_b32_e32 v151, v0
	s_and_b64 vcc, exec, s[6:7]
	v_and_b32_e32 v150, 31, v151
	s_cbranch_vccz .LBB0_753
	s_mov_b64 s[44:45], 0
	s_and_b64 vcc, exec, s[8:9]
	s_mov_b64 s[34:35], 0
	s_cbranch_vccnz .LBB0_754
	v_bfe_u32 v153, v151, 5, 1
	v_lshlrev_b32_e32 v152, 2, v153
	s_and_b64 vcc, exec, s[44:45]
	s_cbranch_vccnz .LBB0_755

.LBB0_759:
	v_readlane_b32 vcc_lo, v255, 1
	s_cmp_lg_u32 vcc_lo, 0
	s_cbranch_scc1 .LBB0_865
	s_mov_b64 s[0:1], exec
	v_readlane_b32 s6, v254, 7
	v_readlane_b32 s7, v254, 8
	s_and_b64 s[6:7], s[0:1], s[6:7]
	s_mov_b64 exec, s[6:7]
	s_cbranch_execz .LBB0_763
	s_mov_b64 s[8:9], exec
	v_mbcnt_lo_u32_b32 v2, s8, 0
	v_mbcnt_hi_u32_b32 v2, s9, v2
	v_cmp_eq_u32_e32 vcc, 0, v2
	s_and_saveexec_b64 s[6:7], vcc
	s_cbranch_execz .LBB0_762
	s_bcnt1_i32_b64 s8, s[8:9]
	v_mov_b32_e32 v4, s8
	global_atomic_add v4, v255, v4, s[86:87] offset:256 sc0

.LBB0_763:
	s_or_b64 exec, exec, s[0:1]
	s_waitcnt lgkmcnt(0)
	s_barrier
	ds_read_b32 v2, v1
	s_movk_i32 s0, 0x7f
	s_waitcnt lgkmcnt(0)
	s_barrier
	v_cmp_lt_i32_e32 vcc, s0, v2
	v_readfirstlane_b32 s56, v2
	s_mov_b64 s[0:1], -1
	s_cbranch_vccnz .LBB0_758
	s_bfe_u32 vcc_lo, s2, 0x10003
	s_lshl_b32 vcc_lo, vcc_lo, 7
	s_add_i32 s56, s56, vcc_lo
	s_ashr_i32 s48, s56, 5
	s_ashr_i32 s49, s48, 31
	s_bfe_u32 s63, s56, 0x30002
	v_mov_b32_e32 v101, v0
	s_lshl_b64 s[52:53], s[48:49], 11
	v_mov_b32_e32 v5, s53
	s_lshl_b32 s34, s63, 7
	v_cmp_lt_i32_e32 vcc, s27, v101
	s_and_saveexec_b64 s[0:1], vcc
	s_xor_b64 s[6:7], exec, s[0:1]
	s_cbranch_execz .LBB0_770
	v_cmp_lt_u32_e64 s[0:1], s50, v101
	s_and_saveexec_b64 s[8:9], s[0:1]
	s_xor_b64 s[8:9], exec, s[8:9]
	s_cbranch_execz .LBB0_767
	s_lshl_b64 s[0:1], s[48:49], 18
	s_add_u32 s0, s14, s0
	s_addc_u32 s1, s15, s1
	s_lshl_b32 s35, s34, 2
	s_add_u32 s0, s0, s35
	v_lshlrev_b32_e32 v22, 2, v101
	s_addc_u32 s1, s1, 0
	v_add_u32_e32 v2, 0xfffffd80, v22
	v_lshl_add_u64 v[6:7], v[2:3], 2, s[0:1]
	v_cmp_gt_u32_e64 s[0:1], s51, v101
	s_nop 1
	v_cndmask_b32_e64 v2, 0, v98, s[0:1]
	v_cndmask_b32_e64 v85, 0, v7, s[0:1]
	v_cndmask_b32_e64 v84, 0, v6, s[0:1]
	v_mov_b64_e32 v[14:15], v[2:3]

.LBB0_868:
	v_readlane_b32 vcc_lo, v255, 2
	s_cmp_lg_u32 vcc_lo, 0
	s_cbranch_scc1 .LBB0_877
	s_mov_b64 s[6:7], exec
	v_readlane_b32 s8, v254, 7
	v_readlane_b32 s9, v254, 8
	s_and_b64 s[8:9], s[6:7], s[8:9]
	s_mov_b64 exec, s[8:9]
	s_cbranch_execz .LBB0_872
	s_mov_b64 s[34:35], exec
	v_mbcnt_lo_u32_b32 v2, s34, 0
	v_mbcnt_hi_u32_b32 v2, s35, v2
	v_cmp_eq_u32_e32 vcc, 0, v2
	s_and_saveexec_b64 s[8:9], vcc
	s_cbranch_execz .LBB0_871
	s_bcnt1_i32_b64 s34, s[34:35]
	v_mov_b32_e32 v3, s34
	global_atomic_add v3, v255, v3, s[86:87] offset:768 sc0

.LBB0_872:
	s_or_b64 exec, exec, s[6:7]
	s_waitcnt lgkmcnt(0)
	s_barrier
	ds_read_b32 v2, v1
	s_movk_i32 s6, 0x7f
	s_waitcnt lgkmcnt(0)
	s_barrier
	v_cmp_lt_i32_e32 vcc, s6, v2
	v_readfirstlane_b32 s8, v2
	s_mov_b64 s[6:7], -1
	s_cbranch_vccnz .LBB0_867
	s_bfe_u32 vcc_lo, s2, 0x10003
	s_lshl_b32 vcc_lo, vcc_lo, 7
	s_add_i32 s8, s8, vcc_lo
	s_and_b32 s47, s8, 1
	s_ashr_i32 s34, s8, 1
	s_lshl_b32 s8, s47, 2
	s_ashr_i32 s35, s34, 31
	s_add_i32 s45, s91, s8
	s_lshl_b32 s8, s34, 3
	v_readlane_b32 s48, v254, 9
	s_lshl_b64 s[6:7], s[34:35], 2
	s_add_i32 s34, s45, s8
	v_readlane_b32 s52, v254, 13
	v_readlane_b32 s53, v254, 14
	v_readlane_b32 s54, v254, 15
	v_readlane_b32 s55, v254, 16
	v_readlane_b32 s56, v254, 17
	v_readlane_b32 s57, v254, 18
	v_readlane_b32 s58, v254, 19
	v_readlane_b32 s59, v254, 20
	v_mov_b32_e32 v130, v0
	s_ashr_i32 s35, s34, 31
	v_readlane_b32 s60, v254, 21
	v_readlane_b32 s61, v254, 22
	v_readlane_b32 s62, v254, 23
	v_readlane_b32 s63, v254, 24
	s_mov_b64 s[52:53], s[56:57]
	s_lshl_b64 s[8:9], s[34:35], 14
	v_bfe_u32 v131, v130, 5, 1
	s_lshl_b64 s[34:35], s[34:35], 16
	s_mov_b64 s[54:55], s[58:59]
	s_add_u32 s34, s54, s34
	v_or_b32_e32 v2, s3, v131
	v_lshlrev_b32_e32 v132, 2, v130
	s_addc_u32 s35, s55, s35
	v_lshlrev_b32_e32 v134, 9, v2
	v_and_b32_e32 v138, 0x7c, v132
	v_lshlrev_b32_e32 v136, 7, v2
	v_lshl_add_u64 v[2:3], s[34:35], 0, v[134:135]
	v_lshlrev_b32_e32 v134, 2, v138
	s_waitcnt vmcnt(2)
	v_lshl_add_u64 v[106:107], v[2:3], 0, v[134:135]
	v_lshl_add_u32 v18, s47, 9, v130
	v_add_co_u32_e32 v26, vcc, s37, v106
	v_ashrrev_i32_e32 v19, 31, v18
	s_nop 0
	v_addc_co_u32_e32 v27, vcc, 0, v107, vcc
	v_lshl_add_u64 v[20:21], v[18:19], 2, s[18:19]
	v_add_co_u32_e32 v22, vcc, s37, v20
	global_load_dwordx4 v[14:17], v[106:107], off nt
	global_load_dwordx4 v[10:13], v[106:107], off offset:1024 nt
	global_load_dwordx4 v[6:9], v[106:107], off offset:2048 nt
	global_load_dwordx4 v[2:5], v[106:107], off offset:3072 nt
	v_addc_co_u32_e32 v23, vcc, 0, v21, vcc
	global_load_dword v116, v[22:23], off
	global_load_dword v117, v[20:21], off
	s_add_u32 s6, s6, 0x4000
	s_addc_u32 s7, s7, 0
	s_lshl_b64 s[34:35], s[6:7], 11
	v_readlane_b32 s49, v254, 10
	s_add_u32 s48, s28, s34
	s_addc_u32 s49, s29, s35
	v_lshlrev_b64 v[30:31], 1, v[18:19]
	v_lshl_add_u64 v[32:33], s[48:49], 0, v[30:31]
	global_load_ushort v118, v[32:33], off
	global_load_dwordx4 v[22:25], v[26:27], off offset:1024 nt
	global_load_dwordx4 v[18:21], v[26:27], off offset:2048 nt
	s_add_u32 s48, s12, s34
	s_addc_u32 s49, s13, s35
	v_lshl_add_u64 v[90:91], s[48:49], 0, v[30:31]
	global_load_ushort v133, v[90:91], off
	v_add_co_u32_e32 v28, vcc, s38, v106
	s_add_u32 s34, s30, s34
	s_nop 0
	v_addc_co_u32_e32 v29, vcc, 0, v107, vcc
	s_addc_u32 s35, s31, s35
	v_lshl_add_u64 v[92:93], s[34:35], 0, v[30:31]
	v_add_co_u32_e32 v30, vcc, s37, v32
	v_and_b32_e32 v157, 0x7f, v130
	s_nop 0
	v_addc_co_u32_e32 v31, vcc, 0, v33, vcc
	global_load_ushort v134, v[92:93], off
	global_load_ushort v140, v[92:93], off offset:2048
	global_load_ushort v141, v[30:31], off
	global_load_ushort v142, v[30:31], off offset:2048
	global_load_ushort v143, v[90:91], off offset:2048
	global_load_ushort v145, v[32:33], off offset:2048
	global_load_dwordx4 v[78:81], v[28:29], off offset:-4096 nt
	global_load_dwordx4 v[74:77], v[28:29], off nt
	global_load_dwordx4 v[70:73], v[28:29], off offset:1024 nt
	global_load_dwordx4 v[66:69], v[28:29], off offset:2048 nt
	v_add_co_u32_e32 v30, vcc, s39, v106
	v_and_or_b32 v132, v132, s44, v157
	s_nop 0
	v_addc_co_u32_e32 v31, vcc, 0, v107, vcc
	v_add_co_u32_e32 v32, vcc, s40, v106
	v_lshl_add_u32 v132, v132, 2, 0
	s_nop 0
	v_addc_co_u32_e32 v33, vcc, 0, v107, vcc
	v_add_co_u32_e32 v108, vcc, s41, v106
	global_load_dwordx4 v[82:85], v[28:29], off offset:3072 nt
	global_load_dwordx4 v[34:37], v[32:33], off offset:-4096 nt
	global_load_dwordx4 v[86:89], v[26:27], off offset:3072 nt
	global_load_dwordx4 v[62:65], v[30:31], off offset:1024 nt
	global_load_dwordx4 v[58:61], v[30:31], off offset:2048 nt
	global_load_dwordx4 v[54:57], v[30:31], off offset:3072 nt
	global_load_dwordx4 v[50:53], v[32:33], off nt
	global_load_dwordx4 v[46:49], v[32:33], off offset:1024 nt
	global_load_dwordx4 v[42:45], v[32:33], off offset:2048 nt
	global_load_dwordx4 v[38:41], v[32:33], off offset:3072 nt
	v_addc_co_u32_e32 v109, vcc, 0, v107, vcc
	v_add_co_u32_e32 v90, vcc, s37, v90
	v_and_b32_e32 v144, 63, v130
	s_nop 0
	v_addc_co_u32_e32 v91, vcc, 0, v91, vcc
	s_waitcnt vmcnt(30)
	v_add_co_u32_e32 v114, vcc, s25, v106
	global_load_ushort v146, v[90:91], off
	s_nop 0
	v_addc_co_u32_e32 v115, vcc, 0, v107, vcc
	v_add_co_u32_e32 v92, vcc, s37, v92
	global_load_dwordx4 v[30:33], v[108:109], off offset:1024 nt
	global_load_dwordx4 v[26:29], v[108:109], off offset:2048 nt
	v_addc_co_u32_e32 v93, vcc, 0, v93, vcc
	global_load_ushort v147, v[92:93], off
	global_load_ushort v148, v[92:93], off offset:2048
	global_load_ushort v149, v[90:91], off offset:2048
	global_load_dwordx4 v[110:113], v[114:115], off offset:-4096 nt
	global_load_dwordx4 v[102:105], v[114:115], off nt
	global_load_dwordx4 v[98:101], v[114:115], off offset:1024 nt
	global_load_dwordx4 v[94:97], v[114:115], off offset:2048 nt
	s_nop 0
	global_load_dwordx4 v[90:93], v[114:115], off offset:3072 nt
	v_lshlrev_b32_e32 v130, 4, v130
	v_and_b32_e32 v130, 0x1f0, v130
	s_mov_b32 s46, 0
	v_readlane_b32 s50, v254, 11
	v_readlane_b32 s51, v254, 12
	s_mov_b64 s[56:57], s[60:61]
	s_mov_b64 s[58:59], s[62:63]
	s_waitcnt vmcnt(35)
	v_sub_f32_e32 v114, v116, v117
	v_mul_f32_e32 v114, 0x3fb8aa3b, v114
	v_exp_f32_e32 v116, v114
	v_add_co_u32_e32 v114, vcc, s42, v106
	v_add_f32_e32 v116, 1.0, v116
	v_rcp_f32_e32 v150, v116
	s_waitcnt vmcnt(34)
	v_lshlrev_b32_e32 v116, 16, v118
	v_max_f32_e32 v116, v116, v116
	v_med3_f32 v116, v116, s43, v139
	v_addc_co_u32_e32 v115, vcc, 0, v107, vcc
	v_mul_f32_e32 v116, 0xbfb8aa3b, v116
	global_load_dwordx4 v[126:129], v[108:109], off offset:3072 nt
	s_nop 0
	global_load_dwordx4 v[106:109], v[114:115], off nt
	v_exp_f32_e32 v151, v116
	global_load_dwordx4 v[122:125], v[114:115], off offset:1024 nt
	global_load_dwordx4 v[118:121], v[114:115], off offset:2048 nt
	s_nop 0
	global_load_dwordx4 v[114:117], v[114:115], off offset:3072 nt
	s_waitcnt vmcnt(36)
	v_lshlrev_b32_e32 v133, 16, v133
	v_mul_f32_e32 v153, 0xbfb8aa3b, v133
	v_exp_f32_e32 v153, v153
	v_add_f32_e32 v151, 1.0, v151
	s_waitcnt vmcnt(31)
	v_lshlrev_b32_e32 v143, 16, v143
	s_waitcnt vmcnt(30)
	v_lshlrev_b32_e32 v145, 16, v145
	v_max_f32_e32 v145, v145, v145
	v_med3_f32 v145, v145, s43, v139
	v_mul_f32_e32 v145, 0xbfb8aa3b, v145
	v_add_f32_e32 v153, 1.0, v153
	v_exp_f32_e32 v145, v145
	v_rcp_f32_e32 v153, v153
	v_lshlrev_b32_e32 v141, 16, v141
	v_rcp_f32_e32 v151, v151
	v_add_f32_e32 v145, 1.0, v145
	v_mul_f32_e32 v133, v153, v133
	v_rcp_f32_e32 v145, v145
	v_mul_f32_e32 v153, 0xbfb8aa3b, v143
	v_max_f32_e32 v141, v141, v141
	v_exp_f32_e32 v153, v153
	v_med3_f32 v141, v141, s43, v139
	v_mul_f32_e32 v141, 0xbfb8aa3b, v141
	v_sub_f32_e32 v152, 1.0, v150
	v_exp_f32_e32 v141, v141
	v_fma_f32 v151, v152, v151, v150
	v_fma_f32 v145, v152, v145, v150
	v_sub_f32_e32 v157, 1.0, v151
	ds_write2st64_b32 v132, v151, v145 offset1:2
	v_add_f32_e32 v151, 1.0, v153
	v_rcp_f32_e32 v151, v151
	v_add_f32_e32 v141, 1.0, v141
	v_rcp_f32_e32 v141, v141
	v_lshlrev_b32_e32 v134, 16, v134
	v_mul_f32_e32 v143, v151, v143
	ds_write2st64_b32 v132, v133, v143 offset0:64 offset1:66
	v_lshlrev_b32_e32 v133, 16, v140
	ds_write2st64_b32 v132, v134, v133 offset0:96 offset1:98
	v_fma_f32 v133, v152, v141, v150
	v_lshlrev_b32_e32 v141, 16, v142
	v_max_f32_e32 v141, v141, v141
	v_med3_f32 v141, v141, s43, v139
	v_mul_f32_e32 v141, 0xbfb8aa3b, v141
	v_exp_f32_e32 v141, v141
	v_sub_f32_e32 v145, 1.0, v145
	s_waitcnt vmcnt(15)
	v_lshlrev_b32_e32 v134, 16, v146
	s_waitcnt vmcnt(10)
	v_lshlrev_b32_e32 v143, 16, v149
	ds_write2st64_b32 v132, v157, v145 offset0:32 offset1:34
	v_mul_f32_e32 v140, 0xbfb8aa3b, v134
	v_add_f32_e32 v141, 1.0, v141
	v_mul_f32_e32 v145, 0xbfb8aa3b, v143
	v_exp_f32_e32 v140, v140
	v_rcp_f32_e32 v141, v141
	v_exp_f32_e32 v145, v145
	v_sub_f32_e32 v142, 1.0, v133
	v_add_f32_e32 v140, 1.0, v140
	v_fmac_f32_e32 v150, v152, v141
	v_add_f32_e32 v141, 1.0, v145
	v_rcp_f32_e32 v140, v140
	v_rcp_f32_e32 v141, v141
	ds_write2st64_b32 v132, v133, v150 offset0:4 offset1:6
	v_sub_f32_e32 v133, 1.0, v150
	v_mul_f32_e32 v134, v140, v134
	ds_write2st64_b32 v132, v142, v133 offset0:36 offset1:38
	v_mul_f32_e32 v133, v141, v143
	v_lshlrev_b32_e32 v140, 16, v147
	ds_write2st64_b32 v132, v134, v133 offset0:68 offset1:70
	v_lshlrev_b32_e32 v133, 16, v148
	v_cmp_lt_i32_e32 vcc, v155, v156
	ds_write2st64_b32 v132, v140, v133 offset0:100 offset1:102
	v_add_u32_e32 v134, s24, v130
	v_cndmask_b32_e32 v132, v154, v155, vcc
	v_add_u32_e32 v146, s26, v130
	v_add_u32_e32 v130, s27, v131
	v_lshlrev_b32_e32 v145, 2, v132
	v_cmp_gt_u32_e32 vcc, 32, v144
	v_lshl_add_u32 v147, v130, 2, 0
	s_waitcnt lgkmcnt(0)
	s_barrier
	s_branch .LBB0_875

.LBB0_881:
	v_readlane_b32 vcc_lo, v255, 2
	s_cmp_lg_u32 vcc_lo, 0
	s_cbranch_scc1 .LBB0_942
	s_mov_b64 s[0:1], exec
	v_readlane_b32 s4, v254, 7
	v_readlane_b32 s5, v254, 8
	s_and_b64 s[4:5], s[0:1], s[4:5]
	s_mov_b64 exec, s[4:5]
	s_cbranch_execz .LBB0_885
	s_mov_b64 s[6:7], exec
	v_mbcnt_lo_u32_b32 v2, s6, 0
	v_mbcnt_hi_u32_b32 v2, s7, v2
	v_cmp_eq_u32_e32 vcc, 0, v2
	s_and_saveexec_b64 s[4:5], vcc
	s_cbranch_execz .LBB0_884
	s_bcnt1_i32_b64 s6, s[6:7]
	v_mov_b32_e32 v3, s6
	global_atomic_add v3, v255, v3, s[86:87] offset:1024 sc0

.LBB0_885:
	s_or_b64 exec, exec, s[0:1]
	s_waitcnt lgkmcnt(0)
	s_barrier
	ds_read_b32 v2, v157
	s_bfe_u32 s0, s2, 0x10003
	s_mulk_i32 s0, 0x88
	s_addk_i32 s0, 0xff
	s_waitcnt lgkmcnt(0)
	s_barrier
	v_cmp_lt_i32_e32 vcc, s0, v2
	v_readfirstlane_b32 s69, v2
	s_mov_b64 s[0:1], -1
	s_cbranch_vccnz .LBB0_880
	s_bfe_u32 vcc_lo, s2, 0x10003
	s_lshl_b32 vcc_lo, vcc_lo, 8
	s_add_i32 s69, s69, vcc_lo
	s_cmpk_lt_i32 s69, 0x200
	s_cbranch_scc0 .LBB0_932
	s_and_b32 s15, s69, 3
	s_ashr_i32 s36, s69, 2
	s_lshl_b32 s10, s15, 3
	s_add_i32 s14, s33, s10
	s_lshl_b32 s0, s36, 5
	s_add_i32 s0, s14, s0
	s_ashr_i32 s37, s36, 31
	s_ashr_i32 s1, s0, 31
	v_readlane_b32 s52, v254, 9
	s_waitcnt vmcnt(4)
	v_mov_b32_e32 v164, v0
	s_lshl_b64 s[4:5], s[36:37], 2
	s_lshl_b64 s[6:7], s[0:1], 15
	v_readlane_b32 s58, v254, 15
	v_readlane_b32 s59, v254, 16
	v_bfe_u32 v167, v164, 5, 1
	s_add_u32 s6, s58, s6
	v_and_b32_e32 v168, 31, v164
	s_addc_u32 s7, s59, s7
	v_lshlrev_b32_e32 v140, 9, v167
	v_lshl_add_u64 v[2:3], s[6:7], 0, v[140:141]
	v_lshlrev_b32_e32 v140, 4, v168
	v_lshl_add_u64 v[94:95], v[2:3], 0, v[140:141]
	v_add_co_u32_e32 v2, vcc, s47, v94
	s_movk_i32 s6, 0x7000
	s_nop 0
	v_addc_co_u32_e32 v3, vcc, 0, v95, vcc
	s_waitcnt vmcnt(1)
	v_add_co_u32_e32 v110, vcc, s48, v94
	global_load_dwordx4 v[90:93], v[94:95], off nt
	global_load_dwordx4 v[86:89], v[94:95], off offset:1024 nt
	global_load_dwordx4 v[82:85], v[94:95], off offset:2048 nt
	global_load_dwordx4 v[78:81], v[94:95], off offset:3072 nt
	v_addc_co_u32_e32 v111, vcc, 0, v95, vcc
	v_add_co_u32_e32 v4, vcc, s49, v94
	global_load_dwordx4 v[74:77], v[2:3], off offset:1024 nt
	global_load_dwordx4 v[70:73], v[2:3], off offset:2048 nt
	global_load_dwordx4 v[66:69], v[110:111], off nt
	global_load_dwordx4 v[62:65], v[110:111], off offset:1024 nt
	global_load_dwordx4 v[58:61], v[110:111], off offset:2048 nt
	global_load_dwordx4 v[54:57], v[110:111], off offset:3072 nt
	v_addc_co_u32_e32 v5, vcc, 0, v95, vcc
	v_add_co_u32_e32 v6, vcc, s50, v94
	s_add_u32 s8, s4, 0x4000
	s_nop 0
	v_addc_co_u32_e32 v7, vcc, 0, v95, vcc
	v_add_co_u32_e32 v96, vcc, s51, v94
	global_load_dwordx4 v[122:125], v[2:3], off offset:3072 nt
	global_load_dwordx4 v[26:29], v[4:5], off offset:1024 nt
	global_load_dwordx4 v[22:25], v[4:5], off offset:2048 nt
	global_load_dwordx4 v[18:21], v[4:5], off offset:3072 nt
	global_load_dwordx4 v[106:109], v[6:7], off offset:-4096 nt
	global_load_dwordx4 v[50:53], v[6:7], off nt
	global_load_dwordx4 v[46:49], v[6:7], off offset:1024 nt
	global_load_dwordx4 v[42:45], v[6:7], off offset:2048 nt
	v_addc_co_u32_e32 v97, vcc, 0, v95, vcc
	s_waitcnt vmcnt(18)
	v_add_co_u32_e32 v38, vcc, s24, v94
	s_movk_i32 s4, 0x17f
	s_nop 0
	v_addc_co_u32_e32 v39, vcc, 0, v95, vcc
	global_load_dwordx4 v[114:117], v[6:7], off offset:3072 nt
	global_load_dwordx4 v[14:17], v[38:39], off offset:-4096 nt
	global_load_dwordx4 v[10:13], v[96:97], off offset:1024 nt
	s_nop 0
	global_load_dwordx4 v[6:9], v[96:97], off offset:2048 nt
	global_load_dwordx4 v[2:5], v[38:39], off nt
	global_load_dwordx4 v[30:33], v[38:39], off offset:1024 nt
	global_load_dwordx4 v[34:37], v[38:39], off offset:2048 nt
	s_nop 0
	global_load_dwordx4 v[38:41], v[38:39], off offset:3072 nt
	v_add_co_u32_e32 v112, vcc, s6, v94
	s_addc_u32 s9, s5, 0
	s_nop 0
	v_addc_co_u32_e32 v113, vcc, 0, v95, vcc
	global_load_dwordx4 v[118:121], v[96:97], off offset:3072 nt
	s_nop 0
	global_load_dwordx4 v[94:97], v[112:113], off nt
	global_load_dwordx4 v[98:101], v[112:113], off offset:1024 nt
	global_load_dwordx4 v[102:105], v[112:113], off offset:2048 nt
	global_load_dwordx4 v[126:129], v[110:111], off offset:-4096 nt
	s_nop 0
	global_load_dwordx4 v[110:113], v[112:113], off offset:3072 nt
	v_cmp_lt_i32_e32 vcc, s4, v164
	v_readlane_b32 s53, v254, 10
	v_readlane_b32 s54, v254, 11
	v_readlane_b32 s55, v254, 12
	v_readlane_b32 s56, v254, 13
	v_readlane_b32 s57, v254, 14
	v_readlane_b32 s60, v254, 17
	v_readlane_b32 s61, v254, 18
	v_readlane_b32 s62, v254, 19
	v_readlane_b32 s63, v254, 20
	v_readlane_b32 s64, v254, 21
	v_readlane_b32 s65, v254, 22
	v_readlane_b32 s66, v254, 23
	v_readlane_b32 s67, v254, 24
	s_and_saveexec_b64 s[4:5], vcc
	s_xor_b64 s[4:5], exec, s[4:5]
	s_cbranch_execz .LBB0_893
	s_movk_i32 s6, 0x1a0
	v_cmp_gt_u32_e32 vcc, s6, v164
	s_and_saveexec_b64 s[6:7], vcc
	s_cbranch_execz .LBB0_892
	v_and_or_b32 v130, v164, 3, s8
	v_mov_b32_e32 v131, s9
	v_lshlrev_b64 v[130:131], 7, v[130:131]
	v_add_u32_e32 v132, 0xfffffe80, v164
	v_lshl_add_u64 v[130:131], s[20:21], 0, v[130:131]
	s_lshl_b32 s18, s10, 2
	v_lshrrev_b32_e32 v133, 2, v132
	v_and_b32_e32 v140, -4, v132
	v_lshl_add_u64 v[130:131], v[130:131], 0, s[18:19]
	v_lshl_add_u64 v[130:131], v[130:131], 0, v[140:141]
	v_add_u32_e32 v140, s10, v133
	global_load_dword v132, v[130:131], off
	v_lshl_add_u64 v[130:131], v[140:141], 2, s[76:77]
	global_load_dword v130, v[130:131], off
	s_mov_b32 s10, 0x41a00000
	s_waitcnt vmcnt(0)
	v_add_f32_e32 v130, v132, v130
	v_cmp_nlt_f32_e32 vcc, s10, v130
	s_and_saveexec_b64 s[10:11], vcc
	s_cbranch_execz .LBB0_891
	v_mul_f32_e32 v130, 0x3fb8aa3b, v130
	v_exp_f32_e32 v139, v130
	s_mov_b32 s12, 0x3f2aaaab
	v_add_f32_e32 v132, 1.0, v139
	v_frexp_mant_f32_e32 v134, v132
	v_cvt_f64_f32_e32 v[130:131], v132
	v_frexp_exp_i32_f64_e32 v130, v[130:131]
	v_cmp_gt_f32_e32 vcc, s12, v134
	v_add_f32_e32 v133, -1.0, v132
	v_sub_f32_e32 v135, v133, v132
	v_subbrev_co_u32_e32 v140, vcc, 0, v130, vcc
	v_sub_u32_e32 v130, 0, v140
	v_sub_f32_e32 v133, v139, v133
	v_add_f32_e32 v135, 1.0, v135
	v_ldexp_f32 v131, v132, v130
	v_add_f32_e32 v133, v133, v135
	v_add_f32_e32 v132, -1.0, v131
	v_add_f32_e32 v134, 1.0, v131
	v_ldexp_f32 v130, v133, v130
	v_add_f32_e32 v133, 1.0, v132
	v_add_f32_e32 v135, -1.0, v134
	v_sub_f32_e32 v133, v131, v133
	v_sub_f32_e32 v131, v131, v135
	v_add_f32_e32 v133, v130, v133
	v_add_f32_e32 v130, v130, v131
	v_add_f32_e32 v143, v134, v130
	v_rcp_f32_e32 v145, v143
	v_sub_f32_e32 v131, v143, v134
	v_sub_f32_e32 v144, v130, v131
	v_add_f32_e32 v131, v132, v133
	v_mul_f32_e32 v147, v131, v145
	v_sub_f32_e32 v130, v131, v132
	v_mul_f32_e32 v132, v143, v147
	v_fma_f32 v134, v147, v143, -v132
	v_fmac_f32_e32 v134, v147, v144
	v_sub_f32_e32 v146, v133, v130
	v_add_f32_e32 v130, v132, v134
	v_sub_f32_e32 v133, v131, v130
	v_pk_add_f32 v[136:137], v[130:131], v[132:133] neg_lo:[0,1] neg_hi:[0,1]
	v_mov_b32_e32 v135, v130
	v_pk_add_f32 v[130:131], v[136:137], v[134:135] neg_lo:[0,1] neg_hi:[0,1]
	s_mov_b32 s12, 0x3f317218
	v_add_f32_e32 v131, v146, v131
	v_add_f32_e32 v130, v130, v131
	v_add_f32_e32 v131, v133, v130
	v_mul_f32_e32 v146, v145, v131
	v_mul_f32_e32 v132, v143, v146
	v_fma_f32 v134, v146, v143, -v132
	v_fmac_f32_e32 v134, v146, v144
	v_sub_f32_e32 v133, v133, v131
	v_add_f32_e32 v143, v130, v133
	v_add_f32_e32 v130, v132, v134
	v_sub_f32_e32 v133, v131, v130
	v_pk_add_f32 v[136:137], v[130:131], v[132:133] neg_lo:[0,1] neg_hi:[0,1]
	v_mov_b32_e32 v135, v130
	v_pk_add_f32 v[130:131], v[136:137], v[134:135] neg_lo:[0,1] neg_hi:[0,1]
	s_nop 0
	v_add_f32_e32 v131, v143, v131
	v_add_f32_e32 v130, v130, v131
	v_add_f32_e32 v131, v147, v146
	v_add_f32_e32 v130, v133, v130
	v_sub_f32_e32 v132, v131, v147
	v_mul_f32_e32 v130, v145, v130
	v_sub_f32_e32 v132, v146, v132
	v_add_f32_e32 v132, v132, v130
	v_add_f32_e32 v134, v131, v132
	v_mul_f32_e32 v135, v134, v134
	v_fmamk_f32 v130, v135, 0x3e9b6dac, v158
	v_fmaak_f32 v143, v135, v130, 0x3f2aaada
	v_cvt_f32_i32_e32 v130, v140
	v_sub_f32_e32 v131, v134, v131
	v_sub_f32_e32 v131, v132, v131
	v_ldexp_f32 v136, v131, 1
	v_mul_f32_e32 v131, v134, v135
	v_ldexp_f32 v133, v134, 1
	v_pk_mul_f32 v[134:135], v[130:131], v[142:143]
	s_nop 0
	v_fma_f32 v132, v130, s12, -v134
	v_fmac_f32_e32 v132, 0xb102e308, v130
	v_pk_add_f32 v[130:131], v[134:135], v[132:133]
	s_mov_b32 s12, 0x7f800000
	v_sub_f32_e32 v133, v131, v133
	v_sub_f32_e32 v133, v135, v133
	v_add_f32_e32 v137, v136, v133
	v_mov_b32_e32 v136, v134
	v_pk_add_f32 v[134:135], v[130:131], v[134:135] neg_lo:[0,1] neg_hi:[0,1]
	v_pk_add_f32 v[144:145], v[130:131], v[136:137]
	v_mov_b32_e32 v133, v130
	v_mov_b32_e32 v135, v145
	v_pk_add_f32 v[146:147], v[132:133], v[134:135] neg_lo:[0,1] neg_hi:[0,1]
	v_pk_add_f32 v[132:133], v[132:133], v[134:135]
	v_mov_b32_e32 v136, v137
	v_pk_add_f32 v[134:135], v[132:133], v[130:131] op_sel:[1,0] op_sel_hi:[0,1] neg_lo:[0,1] neg_hi:[0,1]
	v_pk_add_f32 v[148:149], v[144:145], v[134:135] op_sel_hi:[1,0] neg_lo:[0,1] neg_hi:[0,1]
	v_mov_b32_e32 v144, v145
	v_mov_b32_e32 v145, v133
	v_pk_mov_b32 v[134:135], v[130:131], v[134:135] op_sel:[1,0]
	v_mov_b32_e32 v137, v130
	v_pk_add_f32 v[134:135], v[144:145], v[134:135] neg_lo:[0,1] neg_hi:[0,1]
	v_mov_b32_e32 v148, v146
	v_pk_add_f32 v[130:131], v[136:137], v[134:135] neg_lo:[0,1] neg_hi:[0,1]
	v_mov_b32_e32 v147, v133
	v_pk_add_f32 v[134:135], v[148:149], v[130:131]
	v_cmp_neq_f32_e32 vcc, s12, v139
	v_pk_add_f32 v[136:137], v[134:135], v[134:135] op_sel:[0,1] op_sel_hi:[1,0]
	s_mov_b32 s12, 0x33800000
	v_pk_add_f32 v[132:133], v[132:133], v[136:137] op_sel:[1,0] op_sel_hi:[0,1]
	v_mov_b32_e32 v135, v132
	v_pk_add_f32 v[144:145], v[134:135], v[146:147] neg_lo:[0,1] neg_hi:[0,1]
	v_mov_b32_e32 v131, v136
	v_sub_f32_e32 v133, v134, v144
	v_pk_add_f32 v[130:131], v[130:131], v[144:145] neg_lo:[0,1] neg_hi:[0,1]
	v_sub_f32_e32 v133, v146, v133
	v_add_f32_e32 v130, v130, v133
	v_add_f32_e32 v130, v130, v131
	v_add_f32_e32 v130, v132, v130
	v_cndmask_b32_e32 v130, v159, v130, vcc
	v_cmp_ngt_f32_e32 vcc, -1.0, v139
	s_nop 1
	v_cndmask_b32_e32 v130, v160, v130, vcc
	v_cmp_neq_f32_e32 vcc, -1.0, v139
	s_nop 1
	v_cndmask_b32_e32 v130, v161, v130, vcc
	v_cmp_lt_f32_e64 vcc, |v139|, s12
	s_nop 1
	v_cndmask_b32_e32 v130, v130, v139, vcc

.LBB0_942:
	v_readlane_b32 s0, v255, 1
	s_cmp_eq_u32 s0, 0
	s_cbranch_scc1 .Lp3_done
	s_mov_b32 s0, 0
	s_mov_b32 s1, 1
	v_writelane_b32 v255, s0, 1
	v_writelane_b32 v255, s1, 2
	v_readlane_b32 s91, v254, 46
	s_branch .Lp3_again

	.amdhsa_kernel _Z8skel_fwd4Args
		.amdhsa_group_segment_fixed_size 0
		.amdhsa_private_segment_fixed_size 0
		.amdhsa_kernarg_size 536
		.amdhsa_user_sgpr_count 2
		.amdhsa_user_sgpr_dispatch_ptr 0
		.amdhsa_user_sgpr_queue_ptr 0
		.amdhsa_user_sgpr_kernarg_segment_ptr 1
		.amdhsa_user_sgpr_dispatch_id 0
		.amdhsa_user_sgpr_kernarg_preload_length 0
		.amdhsa_user_sgpr_kernarg_preload_offset 0
		.amdhsa_user_sgpr_private_segment_size 0
		.amdhsa_uses_dynamic_stack 0
		.amdhsa_enable_private_segment 0
		.amdhsa_system_sgpr_workgroup_id_x 1
		.amdhsa_system_sgpr_workgroup_id_y 0
		.amdhsa_system_sgpr_workgroup_id_z 0
		.amdhsa_system_sgpr_workgroup_info 0
		.amdhsa_system_vgpr_workitem_id 0
		.amdhsa_next_free_vgpr 256
		.amdhsa_next_free_sgpr 98
		.amdhsa_accum_offset 256
		.amdhsa_reserve_vcc 1
		.amdhsa_float_round_mode_32 0
		.amdhsa_float_round_mode_16_64 0
		.amdhsa_float_denorm_mode_32 3
		.amdhsa_float_denorm_mode_16_64 3
		.amdhsa_dx10_clamp 1
		.amdhsa_ieee_mode 1
		.amdhsa_fp16_overflow 0
		.amdhsa_tg_split 0
		.amdhsa_exception_fp_ieee_invalid_op 0
		.amdhsa_exception_fp_denorm_src 0
		.amdhsa_exception_fp_ieee_div_zero 0
		.amdhsa_exception_fp_ieee_overflow 0
		.amdhsa_exception_fp_ieee_underflow 0
		.amdhsa_exception_fp_ieee_inexact 0
		.amdhsa_exception_int_div_zero 0
	.end_amdhsa_kernel

amdhsa.kernels:
  - .agpr_count:     0
    .args:
      - .offset:         0
        .size:           280
        .value_kind:     by_value
      - .offset:         280
        .size:           4
        .value_kind:     hidden_block_count_x
      - .offset:         284
        .size:           4
        .value_kind:     hidden_block_count_y
      - .offset:         288
        .size:           4
        .value_kind:     hidden_block_count_z
      - .offset:         292
        .size:           2
        .value_kind:     hidden_group_size_x
      - .offset:         294
        .size:           2
        .value_kind:     hidden_group_size_y
      - .offset:         296
        .size:           2
        .value_kind:     hidden_group_size_z
      - .offset:         298
        .size:           2
        .value_kind:     hidden_remainder_x
      - .offset:         300
        .size:           2
        .value_kind:     hidden_remainder_y
      - .offset:         302
        .size:           2
        .value_kind:     hidden_remainder_z
      - .offset:         320
        .size:           8
        .value_kind:     hidden_global_offset_x
      - .offset:         328
        .size:           8
        .value_kind:     hidden_global_offset_y
      - .offset:         336
        .size:           8
        .value_kind:     hidden_global_offset_z
      - .offset:         344
        .size:           2
        .value_kind:     hidden_grid_dims
      - .offset:         400
        .size:           4
        .value_kind:     hidden_dynamic_lds_size
    .group_segment_fixed_size: 0
    .kernarg_segment_align: 8
    .kernarg_segment_size: 536
    .language:       OpenCL C
    .language_version:
      - 2
      - 0
    .max_flat_workgroup_size: 512
    .name:           _Z8skel_fwd4Args
    .private_segment_fixed_size: 0
    .sgpr_count:     104
    .sgpr_spill_count: 56
    .symbol:         _Z8skel_fwd4Args.kd
    .uniform_work_group_size: 1
    .uses_dynamic_stack: false
    .vgpr_count:     256
    .vgpr_spill_count: 0
    .wavefront_size: 64
